# steady attention loops: m0 save-restore around tile DMAs and redundant self-max ops removed
# speedup vs baseline: 1.0119x; 1.0045x over previous
.LBB0_973:
	s_lshl_b32 s40, s2, 1
	v_add_u32_e32 v216, s40, v242
	ds_read_b64_tr_b16 v[210:211], v216 offset:24576
	ds_read_b64_tr_b16 v[212:213], v216 offset:25088
	s_waitcnt lgkmcnt(9)
	v_mfma_f32_32x32x16_bf16 v[130:145], v[206:209], v[174:177], v[66:81]
	v_add_f32_e32 v114, v98, v99
	v_add_f32_e32 v114, v100, v114
	v_add_f32_e32 v114, v101, v114
	v_add_f32_e32 v114, v102, v114
	v_add_f32_e32 v114, v103, v114
	v_cvt_pk_bf16_f32 v158, v98, v99
	v_cvt_pk_bf16_f32 v159, v100, v101
	ds_read_b64_tr_b16 v[206:207], v216 offset:28672
	ds_read_b64_tr_b16 v[208:209], v216 offset:29184
	v_add_f32_e32 v98, v104, v114
	s_waitcnt lgkmcnt(10)
	v_mfma_f32_32x32x16_bf16 v[114:129], v[202:205], v[174:177], v[66:81]
	v_add_f32_e32 v98, v105, v98
	v_add_f32_e32 v98, v106, v98
	v_add_f32_e32 v146, v107, v98
	v_cvt_pk_bf16_f32 v160, v102, v103
	v_cvt_pk_bf16_f32 v161, v104, v105
	ds_read_b64_tr_b16 v[98:99], v216 offset:25600
	ds_read_b64_tr_b16 v[100:101], v216 offset:26112
	s_waitcnt lgkmcnt(11)
	v_mfma_f32_32x32x16_bf16 v[130:145], v[198:201], v[170:173], v[130:145]
	v_add_f32_e32 v102, v108, v146
	v_add_f32_e32 v102, v109, v102
	v_add_f32_e32 v102, v110, v102
	v_add_f32_e32 v146, v111, v102
	v_cvt_pk_bf16_f32 v154, v106, v107
	v_cvt_pk_bf16_f32 v155, v108, v109
	ds_read_b64_tr_b16 v[102:103], v216 offset:29696
	ds_read_b64_tr_b16 v[104:105], v216 offset:30208
	s_waitcnt lgkmcnt(12)
	v_mfma_f32_32x32x16_bf16 v[114:129], v[194:197], v[170:173], v[114:129]
	v_add_f32_e32 v106, v112, v146
	v_add_f32_e32 v106, v113, v106
	v_add_f32_e32 v106, v82, v106
	v_add_f32_e32 v146, v83, v106
	v_cvt_pk_bf16_f32 v156, v110, v111
	v_cvt_pk_bf16_f32 v157, v112, v113
	ds_read_b64_tr_b16 v[106:107], v216 offset:26624
	ds_read_b64_tr_b16 v[108:109], v216 offset:27136
	s_waitcnt lgkmcnt(13)
	v_mfma_f32_32x32x16_bf16 v[130:145], v[190:193], v[166:169], v[130:145]
	v_add_f32_e32 v110, v84, v146
	v_add_f32_e32 v110, v85, v110
	v_add_f32_e32 v110, v86, v110
	v_add_f32_e32 v146, v87, v110
	v_cvt_pk_bf16_f32 v150, v82, v83
	v_cvt_pk_bf16_f32 v151, v84, v85
	ds_read_b64_tr_b16 v[110:111], v216 offset:30720
	ds_read_b64_tr_b16 v[112:113], v216 offset:31232
	s_waitcnt lgkmcnt(14)
	v_mfma_f32_32x32x16_bf16 v[114:129], v[186:189], v[166:169], v[114:129]
	v_add_f32_e32 v82, v88, v146
	v_add_f32_e32 v82, v89, v82
	v_add_f32_e32 v82, v90, v82
	v_add_f32_e32 v82, v91, v82
	v_cvt_pk_bf16_f32 v152, v86, v87
	v_cvt_pk_bf16_f32 v153, v88, v89
	ds_read_b64_tr_b16 v[86:87], v216 offset:27648
	ds_read_b64_tr_b16 v[88:89], v216 offset:28160
	s_waitcnt lgkmcnt(14)
	v_mfma_f32_32x32x16_bf16 v[130:145], v[182:185], v[162:165], v[130:145]
	v_add_f32_e32 v82, v92, v82
	v_add_f32_e32 v82, v93, v82
	v_add_f32_e32 v82, v94, v82
	v_add_f32_e32 v82, v95, v82
	v_cvt_pk_bf16_f32 v146, v90, v91
	v_cvt_pk_bf16_f32 v147, v92, v93
	ds_read_b64_tr_b16 v[90:91], v216 offset:31744
	ds_read_b64_tr_b16 v[92:93], v216 offset:32256
	v_mfma_f32_32x32x16_bf16 v[114:129], v[178:181], v[162:165], v[114:129]
	v_add_f32_e32 v82, v96, v82
	v_add_f32_e32 v82, v97, v82
	v_add_f32_e32 v84, 0, v82
	v_cvt_pk_bf16_f32 v148, v94, v95
	v_cvt_pk_bf16_f32 v149, v96, v97
	s_waitcnt lgkmcnt(14)
	v_mfma_f32_32x32x16_bf16 v[50:65], v[158:161], v[210:213], v[50:65]
	v_lshl_add_u64 v[218:219], v[226:227], 0, s[16:17]
	v_lshl_add_u64 v[82:83], v[218:219], 0, s[30:31]
	s_add_i32 s2, s46, s83
	v_lshl_add_u64 v[216:217], v[214:215], 0, s[16:17]
	s_mov_b32 m0, s2
	s_nop 0
	global_load_lds_dwordx4 v[82:83], off
	v_lshl_add_u64 v[82:83], v[216:217], 0, s[34:35]
	s_lshl_b32 s2, s44, 1
	s_add_i32 s2, s2, s84
	s_mov_b32 m0, s2
	s_nop 0
	global_load_lds_dwordx4 v[82:83], off
	s_waitcnt lgkmcnt(12)
	v_mfma_f32_32x32x16_bf16 v[34:49], v[158:161], v[206:209], v[34:49]
	v_lshl_add_u64 v[82:83], v[216:217], 0, s[36:37]
	s_addk_i32 s2, 0x2000
	s_mov_b32 m0, s2
	s_nop 0
	global_load_lds_dwordx4 v[82:83], off
	s_waitcnt lgkmcnt(10)
	v_mfma_f32_32x32x16_bf16 v[50:65], v[154:157], v[98:101], v[50:65]
	v_max_f32_e32 v82, v130, v131
	v_max3_f32 v83, v132, v133, v115
	v_max3_f32 v82, v82, v114, v116
	v_max3_f32 v82, v82, v117, v134
	v_max3_f32 v83, v83, v136, v137
	v_max3_f32 v82, v82, v135, v118
	v_max3_f32 v83, v83, v120, v121
	v_max3_f32 v82, v82, v119, v138
	s_waitcnt lgkmcnt(8)
	v_mfma_f32_32x32x16_bf16 v[34:49], v[154:157], v[102:105], v[34:49]
	v_max3_f32 v83, v83, v140, v141
	v_max3_f32 v82, v82, v139, v122
	v_max3_f32 v83, v83, v124, v125
	v_max3_f32 v82, v82, v123, v142
	v_max3_f32 v83, v83, v144, v145
	v_max3_f32 v82, v82, v143, v126
	v_max3_f32 v83, v83, v128, v129
	v_max3_f32 v82, v82, v127, v83
	v_mov_b32_e32 v83, v82
	s_nop 1
	v_permlane32_swap_b32_e32 v82, v83
	v_max_f32_e32 v82, v82, v83
	v_cmp_lt_f32_e32 vcc, s87, v82
	s_cmp_lg_u64 vcc, 0
	v_add_f32_e32 v230, v244, v84
	s_cselect_b64 s[2:3], -1, 0
	s_cbranch_vccnz .LBB0_981

.LBB0_976:
	s_add_i32 s2, s44, 0x2000
	s_cmpk_lg_i32 s44, 0x4000
	s_cselect_b32 s40, s2, 0
	s_lshl_b32 s45, s46, 1
	v_add_u32_e32 v231, s45, v242
	ds_read_b64_tr_b16 v[210:211], v231 offset:24576
	ds_read_b64_tr_b16 v[212:213], v231 offset:25088
	s_waitcnt lgkmcnt(9)
	v_mfma_f32_32x32x16_bf16 v[98:113], v[82:85], v[174:177], v[66:81]
	v_add_f32_e32 v86, v130, v131
	v_add_f32_e32 v86, v132, v86
	v_add_f32_e32 v86, v133, v86
	v_add_f32_e32 v86, v134, v86
	v_add_f32_e32 v86, v135, v86
	v_cvt_pk_bf16_f32 v158, v130, v131
	v_cvt_pk_bf16_f32 v159, v132, v133
	ds_read_b64_tr_b16 v[206:207], v231 offset:28672
	ds_read_b64_tr_b16 v[208:209], v231 offset:29184
	v_add_f32_e32 v82, v136, v86
	v_add_f32_e32 v82, v137, v82
	v_add_f32_e32 v82, v138, v82
	v_add_f32_e32 v146, v139, v82
	s_waitcnt lgkmcnt(10)
	v_mfma_f32_32x32x16_bf16 v[82:97], v[198:201], v[174:177], v[66:81]
	v_cvt_pk_bf16_f32 v160, v134, v135
	v_cvt_pk_bf16_f32 v161, v136, v137
	ds_read_b64_tr_b16 v[130:131], v231 offset:25600
	ds_read_b64_tr_b16 v[132:133], v231 offset:26112
	s_waitcnt lgkmcnt(11)
	v_mfma_f32_32x32x16_bf16 v[98:113], v[202:205], v[170:173], v[98:113]
	v_add_f32_e32 v134, v140, v146
	v_add_f32_e32 v134, v141, v134
	v_add_f32_e32 v134, v142, v134
	v_add_f32_e32 v146, v143, v134
	v_cvt_pk_bf16_f32 v154, v138, v139
	v_cvt_pk_bf16_f32 v155, v140, v141
	ds_read_b64_tr_b16 v[134:135], v231 offset:29696
	ds_read_b64_tr_b16 v[136:137], v231 offset:30208
	s_waitcnt lgkmcnt(12)
	v_mfma_f32_32x32x16_bf16 v[82:97], v[194:197], v[170:173], v[82:97]
	v_add_f32_e32 v138, v144, v146
	v_add_f32_e32 v138, v145, v138
	v_add_f32_e32 v138, v114, v138
	v_add_f32_e32 v146, v115, v138
	v_cvt_pk_bf16_f32 v156, v142, v143
	v_cvt_pk_bf16_f32 v157, v144, v145
	ds_read_b64_tr_b16 v[138:139], v231 offset:26624
	ds_read_b64_tr_b16 v[140:141], v231 offset:27136
	s_waitcnt lgkmcnt(13)
	v_mfma_f32_32x32x16_bf16 v[98:113], v[190:193], v[166:169], v[98:113]
	v_add_f32_e32 v142, v116, v146
	v_add_f32_e32 v142, v117, v142
	v_add_f32_e32 v142, v118, v142
	v_add_f32_e32 v142, v119, v142
	v_cvt_pk_bf16_f32 v150, v114, v115
	v_cvt_pk_bf16_f32 v151, v116, v117
	ds_read_b64_tr_b16 v[114:115], v231 offset:30720
	ds_read_b64_tr_b16 v[116:117], v231 offset:31232
	s_waitcnt lgkmcnt(14)
	v_mfma_f32_32x32x16_bf16 v[82:97], v[186:189], v[166:169], v[82:97]
	v_add_f32_e32 v142, v120, v142
	v_add_f32_e32 v142, v121, v142
	v_add_f32_e32 v142, v122, v142
	v_add_f32_e32 v142, v123, v142
	v_cvt_pk_bf16_f32 v152, v118, v119
	v_cvt_pk_bf16_f32 v153, v120, v121
	ds_read_b64_tr_b16 v[118:119], v231 offset:27648
	ds_read_b64_tr_b16 v[120:121], v231 offset:28160
	s_waitcnt lgkmcnt(14)
	v_mfma_f32_32x32x16_bf16 v[98:113], v[182:185], v[162:165], v[98:113]
	v_add_f32_e32 v142, v124, v142
	v_add_f32_e32 v142, v125, v142
	v_add_f32_e32 v142, v126, v142
	v_add_f32_e32 v142, v127, v142
	v_cvt_pk_bf16_f32 v146, v122, v123
	v_cvt_pk_bf16_f32 v147, v124, v125
	ds_read_b64_tr_b16 v[122:123], v231 offset:31744
	ds_read_b64_tr_b16 v[124:125], v231 offset:32256
	v_mfma_f32_32x32x16_bf16 v[82:97], v[178:181], v[162:165], v[82:97]
	v_add_f32_e32 v142, v128, v142
	v_add_f32_e32 v142, v129, v142
	v_add_f32_e32 v142, 0, v142
	v_cvt_pk_bf16_f32 v148, v126, v127
	v_cvt_pk_bf16_f32 v149, v128, v129
	s_waitcnt lgkmcnt(14)
	v_mfma_f32_32x32x16_bf16 v[50:65], v[158:161], v[210:213], v[50:65]
	s_mov_b64 s[2:3], 0x50000
	v_lshl_add_u64 v[126:127], v[218:219], 0, s[2:3]
	s_add_i32 s2, s44, s83
	s_mov_b32 m0, s2
	s_nop 0
	global_load_lds_dwordx4 v[126:127], off
	s_mov_b64 s[2:3], 0x5830000
	v_lshl_add_u64 v[126:127], v[216:217], 0, s[2:3]
	s_lshl_b32 s2, s40, 1
	s_add_i32 s46, s2, s84
	s_mov_b32 m0, s46
	s_nop 0
	global_load_lds_dwordx4 v[126:127], off
	s_waitcnt lgkmcnt(12)
	v_mfma_f32_32x32x16_bf16 v[34:49], v[158:161], v[206:209], v[34:49]
	s_mov_b64 s[2:3], 0x5830080
	v_lshl_add_u64 v[126:127], v[216:217], 0, s[2:3]
	s_add_i32 s2, s46, 0x2000
	s_mov_b32 m0, s2
	s_nop 0
	global_load_lds_dwordx4 v[126:127], off
	s_waitcnt lgkmcnt(10)
	v_mfma_f32_32x32x16_bf16 v[50:65], v[154:157], v[130:133], v[50:65]
	v_max_f32_e32 v126, v98, v99
	v_max3_f32 v127, v100, v101, v83
	v_max3_f32 v126, v126, v82, v84
	v_max3_f32 v126, v126, v85, v102
	v_max3_f32 v127, v127, v104, v105
	v_max3_f32 v126, v126, v103, v86
	v_max3_f32 v127, v127, v88, v89
	v_max3_f32 v126, v126, v87, v106
	s_waitcnt lgkmcnt(8)
	v_mfma_f32_32x32x16_bf16 v[34:49], v[154:157], v[134:137], v[34:49]
	v_max3_f32 v127, v127, v108, v109
	v_max3_f32 v126, v126, v107, v90
	v_max3_f32 v127, v127, v92, v93
	v_max3_f32 v126, v126, v91, v110
	v_max3_f32 v127, v127, v112, v113
	v_max3_f32 v126, v126, v111, v94
	v_max3_f32 v127, v127, v96, v97
	v_max3_f32 v126, v126, v95, v127
	v_mov_b32_e32 v127, v126
	s_nop 1
	v_permlane32_swap_b32_e32 v126, v127
	v_max_f32_e32 v126, v126, v127
	v_cmp_lt_f32_e32 vcc, s87, v126
	s_cmp_lg_u64 vcc, 0
	v_add_f32_e32 v244, v230, v142
	s_cselect_b64 s[2:3], -1, 0
	s_cbranch_vccnz .LBB0_984

.LBB0_1079:
	s_lshl_b32 s40, s2, 1
	v_add_u32_e32 v216, s40, v242
	ds_read_b64_tr_b16 v[210:211], v216 offset:24576
	ds_read_b64_tr_b16 v[212:213], v216 offset:25088
	s_waitcnt lgkmcnt(9)
	v_mfma_f32_32x32x16_bf16 v[130:145], v[206:209], v[174:177], v[66:81]
	v_add_f32_e32 v114, v98, v99
	v_add_f32_e32 v114, v100, v114
	v_add_f32_e32 v114, v101, v114
	v_add_f32_e32 v114, v102, v114
	v_add_f32_e32 v114, v103, v114
	v_cvt_pk_bf16_f32 v166, v98, v99
	v_cvt_pk_bf16_f32 v167, v100, v101
	ds_read_b64_tr_b16 v[206:207], v216 offset:28672
	ds_read_b64_tr_b16 v[208:209], v216 offset:29184
	v_add_f32_e32 v98, v104, v114
	s_waitcnt lgkmcnt(10)
	v_mfma_f32_32x32x16_bf16 v[114:129], v[198:201], v[174:177], v[66:81]
	v_add_f32_e32 v98, v105, v98
	v_add_f32_e32 v98, v106, v98
	v_add_f32_e32 v154, v107, v98
	v_cvt_pk_bf16_f32 v168, v102, v103
	v_cvt_pk_bf16_f32 v169, v104, v105
	ds_read_b64_tr_b16 v[98:99], v216 offset:25600
	ds_read_b64_tr_b16 v[100:101], v216 offset:26112
	s_waitcnt lgkmcnt(11)
	v_mfma_f32_32x32x16_bf16 v[130:145], v[202:205], v[170:173], v[130:145]
	v_add_f32_e32 v102, v108, v154
	v_add_f32_e32 v102, v109, v102
	v_add_f32_e32 v102, v110, v102
	v_add_f32_e32 v154, v111, v102
	v_cvt_pk_bf16_f32 v162, v106, v107
	v_cvt_pk_bf16_f32 v163, v108, v109
	ds_read_b64_tr_b16 v[102:103], v216 offset:29696
	ds_read_b64_tr_b16 v[104:105], v216 offset:30208
	s_waitcnt lgkmcnt(12)
	v_mfma_f32_32x32x16_bf16 v[114:129], v[194:197], v[170:173], v[114:129]
	v_add_f32_e32 v106, v112, v154
	v_add_f32_e32 v106, v113, v106
	v_add_f32_e32 v106, v82, v106
	v_add_f32_e32 v154, v83, v106
	v_cvt_pk_bf16_f32 v164, v110, v111
	v_cvt_pk_bf16_f32 v165, v112, v113
	ds_read_b64_tr_b16 v[106:107], v216 offset:26624
	ds_read_b64_tr_b16 v[108:109], v216 offset:27136
	s_waitcnt lgkmcnt(13)
	v_mfma_f32_32x32x16_bf16 v[130:145], v[190:193], v[150:153], v[130:145]
	v_add_f32_e32 v110, v84, v154
	v_add_f32_e32 v110, v85, v110
	v_add_f32_e32 v110, v86, v110
	v_add_f32_e32 v154, v87, v110
	v_cvt_pk_bf16_f32 v158, v82, v83
	v_cvt_pk_bf16_f32 v159, v84, v85
	ds_read_b64_tr_b16 v[110:111], v216 offset:30720
	ds_read_b64_tr_b16 v[112:113], v216 offset:31232
	s_waitcnt lgkmcnt(14)
	v_mfma_f32_32x32x16_bf16 v[114:129], v[186:189], v[150:153], v[114:129]
	v_add_f32_e32 v82, v88, v154
	v_add_f32_e32 v82, v89, v82
	v_add_f32_e32 v82, v90, v82
	v_add_f32_e32 v82, v91, v82
	v_cvt_pk_bf16_f32 v160, v86, v87
	v_cvt_pk_bf16_f32 v161, v88, v89
	ds_read_b64_tr_b16 v[86:87], v216 offset:27648
	ds_read_b64_tr_b16 v[88:89], v216 offset:28160
	s_waitcnt lgkmcnt(14)
	v_mfma_f32_32x32x16_bf16 v[130:145], v[182:185], v[146:149], v[130:145]
	v_add_f32_e32 v82, v92, v82
	v_add_f32_e32 v82, v93, v82
	v_add_f32_e32 v82, v94, v82
	v_add_f32_e32 v82, v95, v82
	v_cvt_pk_bf16_f32 v154, v90, v91
	v_cvt_pk_bf16_f32 v155, v92, v93
	ds_read_b64_tr_b16 v[90:91], v216 offset:31744
	ds_read_b64_tr_b16 v[92:93], v216 offset:32256
	v_mfma_f32_32x32x16_bf16 v[114:129], v[178:181], v[146:149], v[114:129]
	v_add_f32_e32 v82, v96, v82
	v_add_f32_e32 v82, v97, v82
	v_add_f32_e32 v84, 0, v82
	v_cvt_pk_bf16_f32 v156, v94, v95
	v_cvt_pk_bf16_f32 v157, v96, v97
	s_waitcnt lgkmcnt(14)
	v_mfma_f32_32x32x16_bf16 v[50:65], v[166:169], v[210:213], v[50:65]
	v_lshl_add_u64 v[218:219], v[226:227], 0, s[34:35]
	v_lshl_add_u64 v[82:83], v[218:219], 0, s[22:23]
	s_add_i32 s2, s48, s44
	v_lshl_add_u64 v[216:217], v[214:215], 0, s[34:35]
	s_mov_b32 m0, s2
	s_nop 0
	global_load_lds_dwordx4 v[82:83], off
	v_lshl_add_u64 v[82:83], v[216:217], 0, s[24:25]
	s_lshl_b32 s2, s43, 1
	s_add_i32 s2, s2, s45
	s_mov_b32 m0, s2
	s_nop 0
	global_load_lds_dwordx4 v[82:83], off
	s_waitcnt lgkmcnt(12)
	v_mfma_f32_32x32x16_bf16 v[34:49], v[166:169], v[206:209], v[34:49]
	v_lshl_add_u64 v[82:83], v[216:217], 0, s[26:27]
	s_addk_i32 s2, 0x2000
	s_mov_b32 m0, s2
	s_nop 0
	global_load_lds_dwordx4 v[82:83], off
	s_waitcnt lgkmcnt(10)
	v_mfma_f32_32x32x16_bf16 v[50:65], v[162:165], v[98:101], v[50:65]
	v_max_f32_e32 v82, v130, v131
	v_max3_f32 v83, v132, v133, v115
	v_max3_f32 v82, v82, v114, v116
	v_max3_f32 v82, v82, v117, v134
	v_max3_f32 v83, v83, v136, v137
	v_max3_f32 v82, v82, v135, v118
	v_max3_f32 v83, v83, v120, v121
	v_max3_f32 v82, v82, v119, v138
	s_waitcnt lgkmcnt(8)
	v_mfma_f32_32x32x16_bf16 v[34:49], v[162:165], v[102:105], v[34:49]
	v_max3_f32 v83, v83, v140, v141
	v_max3_f32 v82, v82, v139, v122
	v_max3_f32 v83, v83, v124, v125
	v_max3_f32 v82, v82, v123, v142
	v_max3_f32 v83, v83, v144, v145
	v_max3_f32 v82, v82, v143, v126
	v_max3_f32 v83, v83, v128, v129
	v_max3_f32 v82, v82, v127, v83
	v_mov_b32_e32 v83, v82
	s_nop 1
	v_permlane32_swap_b32_e32 v82, v83
	v_max_f32_e32 v82, v82, v83
	v_cmp_lt_f32_e32 vcc, s15, v82
	s_cmp_lg_u64 vcc, 0
	v_add_f32_e32 v230, v244, v84
	s_cselect_b64 s[2:3], -1, 0
	s_cbranch_vccnz .LBB0_1087

.LBB0_1082:
	s_add_i32 s2, s43, 0x2000
	s_cmpk_lg_i32 s43, 0x4000
	s_cselect_b32 s40, s2, 0
	s_lshl_b32 s47, s48, 1
	v_add_u32_e32 v231, s47, v242
	ds_read_b64_tr_b16 v[210:211], v231 offset:24576
	ds_read_b64_tr_b16 v[212:213], v231 offset:25088
	s_waitcnt lgkmcnt(9)
	v_mfma_f32_32x32x16_bf16 v[98:113], v[82:85], v[174:177], v[66:81]
	v_add_f32_e32 v86, v130, v131
	v_add_f32_e32 v86, v132, v86
	v_add_f32_e32 v86, v133, v86
	v_add_f32_e32 v86, v134, v86
	v_add_f32_e32 v86, v135, v86
	v_cvt_pk_bf16_f32 v166, v130, v131
	v_cvt_pk_bf16_f32 v167, v132, v133
	ds_read_b64_tr_b16 v[206:207], v231 offset:28672
	ds_read_b64_tr_b16 v[208:209], v231 offset:29184
	v_add_f32_e32 v82, v136, v86
	v_add_f32_e32 v82, v137, v82
	v_add_f32_e32 v82, v138, v82
	v_add_f32_e32 v154, v139, v82
	s_waitcnt lgkmcnt(10)
	v_mfma_f32_32x32x16_bf16 v[82:97], v[198:201], v[174:177], v[66:81]
	v_cvt_pk_bf16_f32 v168, v134, v135
	v_cvt_pk_bf16_f32 v169, v136, v137
	ds_read_b64_tr_b16 v[130:131], v231 offset:25600
	ds_read_b64_tr_b16 v[132:133], v231 offset:26112
	s_waitcnt lgkmcnt(11)
	v_mfma_f32_32x32x16_bf16 v[98:113], v[202:205], v[170:173], v[98:113]
	v_add_f32_e32 v134, v140, v154
	v_add_f32_e32 v134, v141, v134
	v_add_f32_e32 v134, v142, v134
	v_add_f32_e32 v154, v143, v134
	v_cvt_pk_bf16_f32 v162, v138, v139
	v_cvt_pk_bf16_f32 v163, v140, v141
	ds_read_b64_tr_b16 v[134:135], v231 offset:29696
	ds_read_b64_tr_b16 v[136:137], v231 offset:30208
	s_waitcnt lgkmcnt(12)
	v_mfma_f32_32x32x16_bf16 v[82:97], v[194:197], v[170:173], v[82:97]
	v_add_f32_e32 v138, v144, v154
	v_add_f32_e32 v138, v145, v138
	v_add_f32_e32 v138, v114, v138
	v_add_f32_e32 v154, v115, v138
	v_cvt_pk_bf16_f32 v164, v142, v143
	v_cvt_pk_bf16_f32 v165, v144, v145
	ds_read_b64_tr_b16 v[138:139], v231 offset:26624
	ds_read_b64_tr_b16 v[140:141], v231 offset:27136
	s_waitcnt lgkmcnt(13)
	v_mfma_f32_32x32x16_bf16 v[98:113], v[190:193], v[150:153], v[98:113]
	v_add_f32_e32 v142, v116, v154
	v_add_f32_e32 v142, v117, v142
	v_add_f32_e32 v142, v118, v142
	v_add_f32_e32 v142, v119, v142
	v_cvt_pk_bf16_f32 v158, v114, v115
	v_cvt_pk_bf16_f32 v159, v116, v117
	ds_read_b64_tr_b16 v[114:115], v231 offset:30720
	ds_read_b64_tr_b16 v[116:117], v231 offset:31232
	s_waitcnt lgkmcnt(14)
	v_mfma_f32_32x32x16_bf16 v[82:97], v[186:189], v[150:153], v[82:97]
	v_add_f32_e32 v142, v120, v142
	v_add_f32_e32 v142, v121, v142
	v_add_f32_e32 v142, v122, v142
	v_add_f32_e32 v142, v123, v142
	v_cvt_pk_bf16_f32 v160, v118, v119
	v_cvt_pk_bf16_f32 v161, v120, v121
	ds_read_b64_tr_b16 v[118:119], v231 offset:27648
	ds_read_b64_tr_b16 v[120:121], v231 offset:28160
	s_waitcnt lgkmcnt(14)
	v_mfma_f32_32x32x16_bf16 v[98:113], v[182:185], v[146:149], v[98:113]
	v_add_f32_e32 v142, v124, v142
	v_add_f32_e32 v142, v125, v142
	v_add_f32_e32 v142, v126, v142
	v_add_f32_e32 v142, v127, v142
	v_cvt_pk_bf16_f32 v154, v122, v123
	v_cvt_pk_bf16_f32 v155, v124, v125
	ds_read_b64_tr_b16 v[122:123], v231 offset:31744
	ds_read_b64_tr_b16 v[124:125], v231 offset:32256
	v_mfma_f32_32x32x16_bf16 v[82:97], v[178:181], v[146:149], v[82:97]
	v_add_f32_e32 v142, v128, v142
	v_add_f32_e32 v142, v129, v142
	v_add_f32_e32 v142, 0, v142
	v_cvt_pk_bf16_f32 v156, v126, v127
	v_cvt_pk_bf16_f32 v157, v128, v129
	s_waitcnt lgkmcnt(14)
	v_mfma_f32_32x32x16_bf16 v[50:65], v[166:169], v[210:213], v[50:65]
	s_mov_b64 s[2:3], 0x50000
	v_lshl_add_u64 v[126:127], v[218:219], 0, s[2:3]
	s_add_i32 s2, s43, s44
	s_mov_b32 m0, s2
	s_nop 0
	global_load_lds_dwordx4 v[126:127], off
	s_mov_b64 s[2:3], 0x5830000
	v_lshl_add_u64 v[126:127], v[216:217], 0, s[2:3]
	s_lshl_b32 s2, s40, 1
	s_add_i32 s36, s2, s45
	s_mov_b32 m0, s36
	s_nop 0
	global_load_lds_dwordx4 v[126:127], off
	s_waitcnt lgkmcnt(12)
	v_mfma_f32_32x32x16_bf16 v[34:49], v[166:169], v[206:209], v[34:49]
	s_mov_b64 s[2:3], 0x5830080
	v_lshl_add_u64 v[126:127], v[216:217], 0, s[2:3]
	s_add_i32 s2, s36, 0x2000
	s_mov_b32 m0, s2
	s_nop 0
	global_load_lds_dwordx4 v[126:127], off
	s_waitcnt lgkmcnt(10)
	v_mfma_f32_32x32x16_bf16 v[50:65], v[162:165], v[130:133], v[50:65]
	v_max_f32_e32 v126, v98, v99
	v_max3_f32 v127, v100, v101, v83
	v_max3_f32 v126, v126, v82, v84
	v_max3_f32 v126, v126, v85, v102
	v_max3_f32 v127, v127, v104, v105
	v_max3_f32 v126, v126, v103, v86
	v_max3_f32 v127, v127, v88, v89
	v_max3_f32 v126, v126, v87, v106
	s_waitcnt lgkmcnt(8)
	v_mfma_f32_32x32x16_bf16 v[34:49], v[162:165], v[134:137], v[34:49]
	v_max3_f32 v127, v127, v108, v109
	v_max3_f32 v126, v126, v107, v90
	v_max3_f32 v127, v127, v92, v93
	v_max3_f32 v126, v126, v91, v110
	v_max3_f32 v127, v127, v112, v113
	v_max3_f32 v126, v126, v111, v94
	v_max3_f32 v127, v127, v96, v97
	v_max3_f32 v126, v126, v95, v127
	v_mov_b32_e32 v127, v126
	s_nop 1
	v_permlane32_swap_b32_e32 v126, v127
	v_max_f32_e32 v126, v126, v127
	v_cmp_lt_f32_e32 vcc, s15, v126
	s_cmp_lg_u64 vcc, 0
	v_add_f32_e32 v244, v230, v142
	s_cselect_b64 s[2:3], -1, 0
	s_cbranch_vccnz .LBB0_1090
